# E66: E63 with spin-wait back-off shortened (the eight s_sleep 2 sites -> s_sleep 1)
# baseline (speedup 1.0000x reference)
.LBB0_650:
	s_sleep 1
	s_cbranch_execz .LBB0_653
